# P0 x f32->f16 conversion loop: 4 grid-strides per trip (8 loads in flight per lane)
# speedup vs baseline: 1.0027x; 1.0026x over previous
; __device__ __forceinline__ void cvt_copy(const float* src, h16* dst, size_t n8, size_t gt, size_t ngt) {
;     for (size_t i = gt; i < n8; i += ngt) { const f32x4 a = *(const f32x4*)(src + i * 8), b = *(const f32x4*)(src + i * 8 + 4); *(u32x4*)(dst + i * 8) = pg8::pack8(a, b); }
; __device__ __forceinline__ void p0_convert(int wv, const Args& A, LAS unsigned char* lds, int G) {
;     ...
;     cvt_copy(A.in[0], (h16*)(ws + WS_X), (size_t)NP * DM / 8, gt, ngt);
.LBB0_135:
	s_or_b64 exec, exec, s[24:25]
	s_mov_b32 s3, 0
	s_lshl_b64 s[0:1], s[2:3], 9
	v_ashrrev_i32_e32 v3, 31, v2
	v_lshl_add_u64 v[4:5], s[0:1], 0, v[2:3]
	s_ashr_i32 s55, s46, 31
	s_mov_b32 s54, s46
	s_mov_b64 s[0:1], 0x800000
	s_lshl_b64 s[10:11], s[54:55], 9
	v_cmp_gt_u64_e32 vcc, s[0:1], v[4:5]
	v_lshlrev_b64 v[6:7], 5, v[2:3]
	s_and_saveexec_b64 s[6:7], vcc
	s_cbranch_execz .LBB0_138
	s_load_dwordx2 s[0:1], s[84:85], 0x0
	s_lshl_b64 s[4:5], s[2:3], 14
	s_mov_b64 s[14:15], 0
	s_mov_b64 s[16:17], 0x7fffff
	v_mov_b64_e32 v[12:13], v[4:5]
	s_waitcnt lgkmcnt(0)
	s_add_u32 s0, s0, s4
	s_addc_u32 s1, s1, s5
	s_lshl_b64 s[8:9], s[54:55], 14
	s_lshl_b64 s[4:5], s[2:3], 13
	v_lshl_add_u64 v[8:9], s[0:1], 0, v[6:7]
	s_add_u32 s0, s44, s4
	s_addc_u32 s1, s45, s5
	v_lshl_add_u64 v[10:11], v[2:3], 4, s[0:1]
	s_mov_b64 s[0:1], 0xab01000
	v_lshl_add_u64 v[8:9], v[8:9], 0, 16
	v_lshl_add_u64 v[10:11], v[10:11], 0, s[0:1]
	s_lshl_b64 s[12:13], s[54:55], 13
	s_lshl_b64 s[98:99], s[10:11], 1
	s_add_u32 s98, s98, s10
	s_addc_u32 s99, s99, s11
.Lcv4_loop:
	v_lshl_add_u64 v[224:225], v[12:13], 0, s[98:99]
	v_cmp_lt_u64_e32 vcc, s[16:17], v[224:225]
	s_cbranch_vccnz .Lcv4_exit
	v_lshl_add_u64 v[212:213], v[8:9], 0, s[8:9]
	v_lshl_add_u64 v[214:215], v[212:213], 0, s[8:9]
	v_lshl_add_u64 v[216:217], v[214:215], 0, s[8:9]
	global_load_dwordx4 v[180:183], v[8:9], off offset:-16
	global_load_dwordx4 v[184:187], v[8:9], off
	global_load_dwordx4 v[188:191], v[212:213], off offset:-16
	global_load_dwordx4 v[192:195], v[212:213], off
	global_load_dwordx4 v[196:199], v[214:215], off offset:-16
	global_load_dwordx4 v[200:203], v[214:215], off
	global_load_dwordx4 v[204:207], v[216:217], off offset:-16
	global_load_dwordx4 v[208:211], v[216:217], off
	v_lshl_add_u64 v[218:219], v[10:11], 0, s[12:13]
	v_lshl_add_u64 v[220:221], v[218:219], 0, s[12:13]
	v_lshl_add_u64 v[222:223], v[220:221], 0, s[12:13]
	v_lshl_add_u64 v[12:13], v[224:225], 0, s[10:11]
	s_waitcnt vmcnt(6)
	v_cvt_pk_f16_f32 v180, v180, v181
	v_cvt_pk_f16_f32 v181, v182, v183
	v_cvt_pk_f16_f32 v182, v184, v185
	v_cvt_pk_f16_f32 v183, v186, v187
	global_store_dwordx4 v[10:11], v[180:183], off
	s_waitcnt vmcnt(5)
	v_cvt_pk_f16_f32 v188, v188, v189
	v_cvt_pk_f16_f32 v189, v190, v191
	v_cvt_pk_f16_f32 v190, v192, v193
	v_cvt_pk_f16_f32 v191, v194, v195
	global_store_dwordx4 v[218:219], v[188:191], off
	s_waitcnt vmcnt(4)
	v_cvt_pk_f16_f32 v196, v196, v197
	v_cvt_pk_f16_f32 v197, v198, v199
	v_cvt_pk_f16_f32 v198, v200, v201
	v_cvt_pk_f16_f32 v199, v202, v203
	global_store_dwordx4 v[220:221], v[196:199], off
	s_waitcnt vmcnt(3)
	v_cvt_pk_f16_f32 v204, v204, v205
	v_cvt_pk_f16_f32 v205, v206, v207
	v_cvt_pk_f16_f32 v206, v208, v209
	v_cvt_pk_f16_f32 v207, v210, v211
	global_store_dwordx4 v[222:223], v[204:207], off
	v_lshl_add_u64 v[8:9], v[216:217], 0, s[8:9]
	v_lshl_add_u64 v[10:11], v[222:223], 0, s[12:13]
	s_branch .Lcv4_loop
.Lcv4_exit:
	v_cmp_ge_u64_e32 vcc, s[16:17], v[12:13]
	s_and_b64 exec, exec, vcc
	s_cbranch_execz .LBB0_138
